# GEMM tile boundary: leading wave half runs its epilogue during the trailing half's last MFMA block (align barrier moved after the epilogue), IN and OUT
# speedup vs baseline: 1.0093x; 1.0093x over previous
.Lin_zskip:
.LBB0_140:
	s_add_u32 s10, s8, 0xfff80080
	s_addc_u32 s11, s9, -1
	s_add_i32 s60, 0, 0x10000
	s_cmp_eq_u32 s59, 28
	s_cselect_b32 s15, s0, s11
	s_cselect_b32 s14, s1, s10
	v_add_u32_e32 v0, s60, v167
	s_cselect_b32 s11, s25, s58
	s_cselect_b32 s10, s27, s57
	s_add_i32 s62, 0, 0x14000
	ds_read_b128 v[130:133], v0
	ds_read_b128 v[158:161], v0 offset:1024
	ds_read_b128 v[162:165], v0 offset:2048
	ds_read_b128 v[170:173], v0 offset:3072
	v_add_u32_e32 v0, s62, v167
	ds_read_b128 v[174:177], v0
	ds_read_b128 v[178:181], v0 offset:1024
	ds_read_b128 v[182:185], v0 offset:2048
	ds_read_b128 v[186:189], v0 offset:3072
	s_mov_b32 m0, s52
	s_nop 0
	global_load_lds_dwordx4 v140, s[74:75]
	s_mov_b32 m0, s53
	s_nop 0
	global_load_lds_dwordx4 v136, s[74:75]
	s_add_i32 m0, s48, 0xc000
	ds_read_b128 v[190:193], v169
	ds_read_b128 v[194:197], v169 offset:1024
	ds_read_b128 v[198:201], v169 offset:2048
	ds_read_b128 v[216:219], v169 offset:3072
	ds_read_b128 v[220:223], v169 offset:4096
	ds_read_b128 v[224:227], v169 offset:5120
	ds_read_b128 v[228:231], v169 offset:6144
	ds_read_b128 v[232:235], v169 offset:7168
	global_load_lds_dwordx4 v156, s[8:9]
	s_add_i32 m0, s48, 0xe000
	s_nop 0
	global_load_lds_dwordx4 v146, s[8:9]
	s_waitcnt vmcnt(8)
	s_waitcnt lgkmcnt(0)
	s_barrier
	s_setprio 1
	s_waitcnt lgkmcnt(0)
	v_mfma_f32_16x16x32_bf16 v[126:129], v[130:133], v[190:193], v[126:129]
	v_mfma_f32_16x16x32_bf16 v[122:125], v[162:165], v[190:193], v[122:125]
	v_mfma_f32_16x16x32_bf16 v[110:113], v[130:133], v[198:201], v[110:113]
	v_mfma_f32_16x16x32_bf16 v[106:109], v[162:165], v[198:201], v[106:109]
	v_mfma_f32_16x16x32_bf16 v[94:97], v[130:133], v[220:223], v[94:97]
	v_mfma_f32_16x16x32_bf16 v[90:93], v[162:165], v[220:223], v[90:93]
	v_mfma_f32_16x16x32_bf16 v[78:81], v[130:133], v[228:231], v[78:81]
	v_mfma_f32_16x16x32_bf16 v[74:77], v[162:165], v[228:231], v[74:77]
	v_mfma_f32_16x16x32_bf16 v[126:129], v[158:161], v[194:197], v[126:129]
	v_mfma_f32_16x16x32_bf16 v[122:125], v[170:173], v[194:197], v[122:125]
	v_mfma_f32_16x16x32_bf16 v[110:113], v[158:161], v[216:219], v[110:113]
	v_mfma_f32_16x16x32_bf16 v[106:109], v[170:173], v[216:219], v[106:109]
	v_mfma_f32_16x16x32_bf16 v[94:97], v[158:161], v[224:227], v[94:97]
	v_mfma_f32_16x16x32_bf16 v[90:93], v[170:173], v[224:227], v[90:93]
	v_mfma_f32_16x16x32_bf16 v[78:81], v[158:161], v[232:235], v[78:81]
	v_mfma_f32_16x16x32_bf16 v[74:77], v[170:173], v[232:235], v[74:77]
	s_setprio 0
	s_setprio 1
	v_mfma_f32_16x16x32_bf16 v[118:121], v[174:177], v[190:193], v[118:121]
	v_mfma_f32_16x16x32_bf16 v[114:117], v[182:185], v[190:193], v[114:117]
	v_mfma_f32_16x16x32_bf16 v[102:105], v[174:177], v[198:201], v[102:105]
	v_mfma_f32_16x16x32_bf16 v[98:101], v[182:185], v[198:201], v[98:101]
	v_mfma_f32_16x16x32_bf16 v[86:89], v[174:177], v[220:223], v[86:89]
	v_mfma_f32_16x16x32_bf16 v[82:85], v[182:185], v[220:223], v[82:85]
	v_mfma_f32_16x16x32_bf16 v[70:73], v[174:177], v[228:231], v[70:73]
	v_mfma_f32_16x16x32_bf16 v[66:69], v[182:185], v[228:231], v[66:69]
	v_mfma_f32_16x16x32_bf16 v[118:121], v[178:181], v[194:197], v[118:121]
	v_mfma_f32_16x16x32_bf16 v[114:117], v[186:189], v[194:197], v[114:117]
	v_mfma_f32_16x16x32_bf16 v[102:105], v[178:181], v[216:219], v[102:105]
	v_mfma_f32_16x16x32_bf16 v[98:101], v[186:189], v[216:219], v[98:101]
	v_mfma_f32_16x16x32_bf16 v[86:89], v[178:181], v[224:227], v[86:89]
	v_mfma_f32_16x16x32_bf16 v[82:85], v[186:189], v[224:227], v[82:85]
	v_mfma_f32_16x16x32_bf16 v[70:73], v[178:181], v[232:235], v[70:73]
	v_mfma_f32_16x16x32_bf16 v[66:69], v[186:189], v[232:235], v[66:69]
	s_setprio 0
	s_barrier
	s_add_i32 s60, s60, s29
	s_add_u32 s72, s10, s44
	s_addc_u32 s73, s11, s45
	s_mov_b32 m0, s60
	ds_read_b128 v[190:193], v169 offset:16384
	ds_read_b128 v[194:197], v169 offset:17408
	ds_read_b128 v[198:201], v169 offset:18432
	ds_read_b128 v[216:219], v169 offset:19456
	ds_read_b128 v[220:223], v169 offset:20480
	ds_read_b128 v[224:227], v169 offset:21504
	ds_read_b128 v[228:231], v169 offset:22528
	ds_read_b128 v[232:235], v169 offset:23552
	global_load_lds_dwordx4 v138, s[10:11]
	s_add_i32 m0, s60, 0x2000
	s_add_u32 s60, s10, 0x80000
	s_addc_u32 s61, s11, 0
	s_add_i32 s62, s62, s29
	global_load_lds_dwordx4 v134, s[10:11]
	s_mov_b32 m0, s62
	s_add_u32 s74, s14, s44
	s_addc_u32 s75, s15, s45
	global_load_lds_dwordx4 v138, s[60:61]
	s_add_i32 m0, s62, 0x2000
	s_nop 0
	global_load_lds_dwordx4 v134, s[60:61]
	s_waitcnt vmcnt(6)
	s_waitcnt lgkmcnt(0)
	s_barrier
	s_setprio 1
	s_waitcnt lgkmcnt(0)
	v_mfma_f32_16x16x32_bf16 v[62:65], v[130:133], v[190:193], v[62:65]
	v_mfma_f32_16x16x32_bf16 v[58:61], v[162:165], v[190:193], v[58:61]
	v_mfma_f32_16x16x32_bf16 v[46:49], v[130:133], v[198:201], v[46:49]
	v_mfma_f32_16x16x32_bf16 v[42:45], v[162:165], v[198:201], v[42:45]
	v_mfma_f32_16x16x32_bf16 v[30:33], v[130:133], v[220:223], v[30:33]
	v_mfma_f32_16x16x32_bf16 v[26:29], v[162:165], v[220:223], v[26:29]
	v_mfma_f32_16x16x32_bf16 v[14:17], v[130:133], v[228:231], v[14:17]
	v_mfma_f32_16x16x32_bf16 v[10:13], v[162:165], v[228:231], v[10:13]
	v_mfma_f32_16x16x32_bf16 v[62:65], v[158:161], v[194:197], v[62:65]
	v_mfma_f32_16x16x32_bf16 v[58:61], v[170:173], v[194:197], v[58:61]
	v_mfma_f32_16x16x32_bf16 v[46:49], v[158:161], v[216:219], v[46:49]
	v_mfma_f32_16x16x32_bf16 v[42:45], v[170:173], v[216:219], v[42:45]
	v_mfma_f32_16x16x32_bf16 v[30:33], v[158:161], v[224:227], v[30:33]
	v_mfma_f32_16x16x32_bf16 v[26:29], v[170:173], v[224:227], v[26:29]
	v_mfma_f32_16x16x32_bf16 v[14:17], v[158:161], v[232:235], v[14:17]
	v_mfma_f32_16x16x32_bf16 v[10:13], v[170:173], v[232:235], v[10:13]
	s_setprio 0
	s_setprio 1
	v_mfma_f32_16x16x32_bf16 v[54:57], v[174:177], v[190:193], v[54:57]
	v_mfma_f32_16x16x32_bf16 v[50:53], v[182:185], v[190:193], v[50:53]
	v_mfma_f32_16x16x32_bf16 v[38:41], v[174:177], v[198:201], v[38:41]
	v_mfma_f32_16x16x32_bf16 v[34:37], v[182:185], v[198:201], v[34:37]
	v_mfma_f32_16x16x32_bf16 v[22:25], v[174:177], v[220:223], v[22:25]
	v_mfma_f32_16x16x32_bf16 v[18:21], v[182:185], v[220:223], v[18:21]
	v_mfma_f32_16x16x32_bf16 v[6:9], v[174:177], v[228:231], v[6:9]
	v_mfma_f32_16x16x32_bf16 v[2:5], v[182:185], v[228:231], v[2:5]
	v_mfma_f32_16x16x32_bf16 v[54:57], v[178:181], v[194:197], v[54:57]
	v_mfma_f32_16x16x32_bf16 v[50:53], v[186:189], v[194:197], v[50:53]
	v_mfma_f32_16x16x32_bf16 v[38:41], v[178:181], v[216:219], v[38:41]
	v_mfma_f32_16x16x32_bf16 v[34:37], v[186:189], v[216:219], v[34:37]
	v_mfma_f32_16x16x32_bf16 v[22:25], v[178:181], v[224:227], v[22:25]
	v_mfma_f32_16x16x32_bf16 v[18:21], v[186:189], v[224:227], v[18:21]
	v_mfma_f32_16x16x32_bf16 v[6:9], v[178:181], v[232:235], v[6:9]
	v_mfma_f32_16x16x32_bf16 v[2:5], v[186:189], v[232:235], v[2:5]
	s_setprio 0
	s_barrier
	s_add_i32 s60, 0, 0x18000
	v_add_u32_e32 v0, s60, v167
	s_add_i32 s61, 0, 0x1c000
	ds_read_b128 v[130:133], v0
	ds_read_b128 v[158:161], v0 offset:1024
	ds_read_b128 v[162:165], v0 offset:2048
	ds_read_b128 v[170:173], v0 offset:3072
	v_add_u32_e32 v0, s61, v167
	ds_read_b128 v[174:177], v0
	ds_read_b128 v[178:181], v0 offset:1024
	ds_read_b128 v[182:185], v0 offset:2048
	ds_read_b128 v[186:189], v0 offset:3072
	s_mov_b32 m0, s48
	s_nop 0
	global_load_lds_dwordx4 v140, s[14:15]
	s_mov_b32 m0, s49
	s_nop 0
	global_load_lds_dwordx4 v136, s[14:15]
	s_add_u32 s14, s14, 0x80000
	s_addc_u32 s15, s15, 0
	s_mov_b32 m0, s50
	ds_read_b128 v[190:193], v169 offset:32768
	ds_read_b128 v[194:197], v169 offset:33792
	ds_read_b128 v[198:201], v169 offset:34816
	ds_read_b128 v[216:219], v169 offset:35840
	ds_read_b128 v[220:223], v169 offset:36864
	ds_read_b128 v[224:227], v169 offset:37888
	ds_read_b128 v[228:231], v169 offset:38912
	ds_read_b128 v[232:235], v169 offset:39936
	global_load_lds_dwordx4 v140, s[14:15]
	s_mov_b32 m0, s51
	s_nop 0
	global_load_lds_dwordx4 v136, s[14:15]
	s_waitcnt vmcnt(8)
	s_waitcnt lgkmcnt(0)
	s_barrier
	s_setprio 1
	s_waitcnt lgkmcnt(0)
	v_mfma_f32_16x16x32_bf16 v[126:129], v[130:133], v[190:193], v[126:129]
	v_mfma_f32_16x16x32_bf16 v[122:125], v[162:165], v[190:193], v[122:125]
	v_mfma_f32_16x16x32_bf16 v[110:113], v[130:133], v[198:201], v[110:113]
	v_mfma_f32_16x16x32_bf16 v[106:109], v[162:165], v[198:201], v[106:109]
	v_mfma_f32_16x16x32_bf16 v[94:97], v[130:133], v[220:223], v[94:97]
	v_mfma_f32_16x16x32_bf16 v[90:93], v[162:165], v[220:223], v[90:93]
	v_mfma_f32_16x16x32_bf16 v[78:81], v[130:133], v[228:231], v[78:81]
	v_mfma_f32_16x16x32_bf16 v[74:77], v[162:165], v[228:231], v[74:77]
	v_mfma_f32_16x16x32_bf16 v[126:129], v[158:161], v[194:197], v[126:129]
	v_mfma_f32_16x16x32_bf16 v[122:125], v[170:173], v[194:197], v[122:125]
	v_mfma_f32_16x16x32_bf16 v[110:113], v[158:161], v[216:219], v[110:113]
	v_mfma_f32_16x16x32_bf16 v[106:109], v[170:173], v[216:219], v[106:109]
	v_mfma_f32_16x16x32_bf16 v[94:97], v[158:161], v[224:227], v[94:97]
	v_mfma_f32_16x16x32_bf16 v[90:93], v[170:173], v[224:227], v[90:93]
	v_mfma_f32_16x16x32_bf16 v[78:81], v[158:161], v[232:235], v[78:81]
	v_mfma_f32_16x16x32_bf16 v[74:77], v[170:173], v[232:235], v[74:77]
	s_setprio 0
	s_setprio 1
	v_mfma_f32_16x16x32_bf16 v[118:121], v[174:177], v[190:193], v[118:121]
	v_mfma_f32_16x16x32_bf16 v[114:117], v[182:185], v[190:193], v[114:117]
	v_mfma_f32_16x16x32_bf16 v[102:105], v[174:177], v[198:201], v[102:105]
	v_mfma_f32_16x16x32_bf16 v[98:101], v[182:185], v[198:201], v[98:101]
	v_mfma_f32_16x16x32_bf16 v[86:89], v[174:177], v[220:223], v[86:89]
	v_mfma_f32_16x16x32_bf16 v[82:85], v[182:185], v[220:223], v[82:85]
	v_mfma_f32_16x16x32_bf16 v[70:73], v[174:177], v[228:231], v[70:73]
	v_mfma_f32_16x16x32_bf16 v[66:69], v[182:185], v[228:231], v[66:69]
	v_mfma_f32_16x16x32_bf16 v[118:121], v[178:181], v[194:197], v[118:121]
	v_mfma_f32_16x16x32_bf16 v[114:117], v[186:189], v[194:197], v[114:117]
	v_mfma_f32_16x16x32_bf16 v[102:105], v[178:181], v[216:219], v[102:105]
	v_mfma_f32_16x16x32_bf16 v[98:101], v[186:189], v[216:219], v[98:101]
	v_mfma_f32_16x16x32_bf16 v[86:89], v[178:181], v[224:227], v[86:89]
	v_mfma_f32_16x16x32_bf16 v[82:85], v[186:189], v[224:227], v[82:85]
	v_mfma_f32_16x16x32_bf16 v[70:73], v[178:181], v[232:235], v[70:73]
	v_mfma_f32_16x16x32_bf16 v[66:69], v[186:189], v[232:235], v[66:69]
	s_setprio 0
	s_barrier
	s_add_i32 s14, s60, s29
	s_mov_b32 m0, s14
	ds_read_b128 v[190:193], v169 offset:49152
	ds_read_b128 v[194:197], v169 offset:50176
	ds_read_b128 v[198:201], v169 offset:51200
	ds_read_b128 v[216:219], v169 offset:52224
	ds_read_b128 v[220:223], v169 offset:53248
	ds_read_b128 v[224:227], v169 offset:54272
	ds_read_b128 v[228:231], v169 offset:55296
	ds_read_b128 v[232:235], v169 offset:56320
	global_load_lds_dwordx4 v138, s[72:73]
	s_add_i32 m0, s14, 0x2000
	s_add_u32 s10, s10, 0x80080
	s_addc_u32 s11, s11, 0
	s_add_i32 s14, s61, s29
	global_load_lds_dwordx4 v134, s[72:73]
	s_mov_b32 m0, s14
	s_nop 0
	global_load_lds_dwordx4 v138, s[10:11]
	s_add_i32 m0, s14, 0x2000
	s_nop 0
	global_load_lds_dwordx4 v134, s[10:11]
	s_waitcnt vmcnt(6)
	s_waitcnt lgkmcnt(0)
	s_barrier
	s_setprio 1
	s_waitcnt lgkmcnt(0)
	v_mfma_f32_16x16x32_bf16 v[62:65], v[130:133], v[190:193], v[62:65]
	v_mfma_f32_16x16x32_bf16 v[58:61], v[162:165], v[190:193], v[58:61]
	v_mfma_f32_16x16x32_bf16 v[46:49], v[130:133], v[198:201], v[46:49]
	v_mfma_f32_16x16x32_bf16 v[42:45], v[162:165], v[198:201], v[42:45]
	v_mfma_f32_16x16x32_bf16 v[30:33], v[130:133], v[220:223], v[30:33]
	v_mfma_f32_16x16x32_bf16 v[26:29], v[162:165], v[220:223], v[26:29]
	v_mfma_f32_16x16x32_bf16 v[14:17], v[130:133], v[228:231], v[14:17]
	v_mfma_f32_16x16x32_bf16 v[10:13], v[162:165], v[228:231], v[10:13]
	v_mfma_f32_16x16x32_bf16 v[62:65], v[158:161], v[194:197], v[62:65]
	v_mfma_f32_16x16x32_bf16 v[58:61], v[170:173], v[194:197], v[58:61]
	v_mfma_f32_16x16x32_bf16 v[46:49], v[158:161], v[216:219], v[46:49]
	v_mfma_f32_16x16x32_bf16 v[42:45], v[170:173], v[216:219], v[42:45]
	v_mfma_f32_16x16x32_bf16 v[30:33], v[158:161], v[224:227], v[30:33]
	v_mfma_f32_16x16x32_bf16 v[26:29], v[170:173], v[224:227], v[26:29]
	v_mfma_f32_16x16x32_bf16 v[14:17], v[158:161], v[232:235], v[14:17]
	v_mfma_f32_16x16x32_bf16 v[10:13], v[170:173], v[232:235], v[10:13]
	s_setprio 0
	s_setprio 1
	v_mfma_f32_16x16x32_bf16 v[54:57], v[174:177], v[190:193], v[54:57]
	v_mfma_f32_16x16x32_bf16 v[50:53], v[182:185], v[190:193], v[50:53]
	v_mfma_f32_16x16x32_bf16 v[38:41], v[174:177], v[198:201], v[38:41]
	v_mfma_f32_16x16x32_bf16 v[34:37], v[182:185], v[198:201], v[34:37]
	v_mfma_f32_16x16x32_bf16 v[22:25], v[174:177], v[220:223], v[22:25]
	v_mfma_f32_16x16x32_bf16 v[18:21], v[182:185], v[220:223], v[18:21]
	v_mfma_f32_16x16x32_bf16 v[6:9], v[174:177], v[228:231], v[6:9]
	v_mfma_f32_16x16x32_bf16 v[2:5], v[182:185], v[228:231], v[2:5]
	v_mfma_f32_16x16x32_bf16 v[54:57], v[178:181], v[194:197], v[54:57]
	v_mfma_f32_16x16x32_bf16 v[50:53], v[186:189], v[194:197], v[50:53]
	v_mfma_f32_16x16x32_bf16 v[38:41], v[178:181], v[216:219], v[38:41]
	v_mfma_f32_16x16x32_bf16 v[34:37], v[186:189], v[216:219], v[34:37]
	v_mfma_f32_16x16x32_bf16 v[22:25], v[178:181], v[224:227], v[22:25]
	v_mfma_f32_16x16x32_bf16 v[18:21], v[186:189], v[224:227], v[18:21]
	v_mfma_f32_16x16x32_bf16 v[6:9], v[178:181], v[232:235], v[6:9]
	v_mfma_f32_16x16x32_bf16 v[2:5], v[186:189], v[232:235], v[2:5]
	s_setprio 0
	s_barrier
	s_add_i32 s59, s59, 2
	s_add_u32 s57, s57, 0x100
	s_addc_u32 s58, s58, 0
	s_add_u32 s8, s8, 0x100
	s_addc_u32 s9, s9, 0
	s_cmp_gt_u32 s59, 29
	s_cbranch_scc0 .LBB0_140
	s_and_b64 vcc, exec, s[20:21]
	s_cbranch_vccz .LBB0_143
.LBB0_143:
	s_add_i32 s0, s55, -12
	s_cmp_lt_u32 s0, 6
	v_lshl_add_u32 v170, s56, 8, v166
	v_mov_b32_e32 v160, 1.0
	v_mov_b32_e32 v161, 0
	s_cselect_b64 s[10:11], -1, 0
	s_cmp_gt_u32 s0, 5
	v_mov_b32_e32 v165, 0
	v_mov_b32_e32 v131, 0
	v_mov_b32_e32 v163, 0
	v_mov_b32_e32 v133, 0
	v_mov_b32_e32 v164, 1.0
	v_mov_b32_e32 v130, 1.0
	v_mov_b32_e32 v162, 1.0
	v_mov_b32_e32 v132, 1.0
	s_cbranch_scc1 .Lepi_fast
	v_mov_b32_e32 v245, 0
	v_lshl_or_b32 v158, s55, 8, v168
	v_ashrrev_i32_e32 v159, 31, v158
	v_lshlrev_b32_e32 v244, 8, v170
	v_and_b32_e32 v244, 0x7ff00, v244
	v_lshl_add_u64 v[246:247], v[142:143], 0, v[244:245]
	global_load_dwordx4 v[184:187], v[246:247], off
	v_lshl_add_u64 v[246:247], v[144:145], 0, v[244:245]
	global_load_dwordx4 v[188:191], v[246:247], off
	v_add_u32_e32 v244, 16, v170
	v_lshlrev_b32_e32 v244, 8, v244
	v_and_b32_e32 v244, 0x7ff00, v244
	v_lshl_add_u64 v[246:247], v[142:143], 0, v[244:245]
	global_load_dwordx4 v[192:195], v[246:247], off
	v_lshl_add_u64 v[246:247], v[144:145], 0, v[244:245]
	global_load_dwordx4 v[196:199], v[246:247], off
	v_add_u32_e32 v244, 32, v170
	v_lshlrev_b32_e32 v244, 8, v244
	v_and_b32_e32 v244, 0x7ff00, v244
	v_lshl_add_u64 v[246:247], v[142:143], 0, v[244:245]
	global_load_dwordx4 v[200:203], v[246:247], off
	v_lshl_add_u64 v[246:247], v[144:145], 0, v[244:245]
	global_load_dwordx4 v[216:219], v[246:247], off
	v_add_u32_e32 v244, 48, v170
	v_lshlrev_b32_e32 v244, 8, v244
	v_and_b32_e32 v244, 0x7ff00, v244
	v_lshl_add_u64 v[246:247], v[142:143], 0, v[244:245]
	global_load_dwordx4 v[220:223], v[246:247], off
	v_lshl_add_u64 v[246:247], v[144:145], 0, v[244:245]
	global_load_dwordx4 v[224:227], v[246:247], off
	v_add_u32_e32 v244, 0x80, v170
	v_lshlrev_b32_e32 v244, 8, v244
	v_and_b32_e32 v244, 0x7ff00, v244
	v_lshl_add_u64 v[246:247], v[142:143], 0, v[244:245]
	global_load_dwordx4 v[228:231], v[246:247], off
	v_lshl_add_u64 v[246:247], v[144:145], 0, v[244:245]
	global_load_dwordx4 v[232:235], v[246:247], off
	v_add_u32_e32 v244, 0x90, v170
	v_lshlrev_b32_e32 v244, 8, v244
	v_and_b32_e32 v244, 0x7ff00, v244
	v_lshl_add_u64 v[246:247], v[142:143], 0, v[244:245]
	global_load_dwordx4 v[236:239], v[246:247], off
	v_lshl_add_u64 v[246:247], v[144:145], 0, v[244:245]
	global_load_dwordx4 v[240:243], v[246:247], off
	s_waitcnt vmcnt(10)
	v_mov_b64_e32 v[182:183], s[12:13]
	v_mad_i64_i32 v[182:183], s[0:1], v170, s43, v[182:183]
	v_lshl_add_u64 v[182:183], v[158:159], 1, v[182:183]
	v_pk_mul_f32 v[160:161], v[126:127], v[188:189] op_sel:[0,0] op_sel_hi:[1,0]
	v_pk_fma_f32 v[126:127], v[126:127], v[184:185], v[160:161] op_sel:[1,0,0] op_sel_hi:[0,0,1] neg_lo:[0,1,0]
	v_pk_mul_f32 v[162:163], v[128:129], v[188:189] op_sel:[0,1] op_sel_hi:[1,1]
	v_pk_fma_f32 v[128:129], v[128:129], v[184:185], v[162:163] op_sel:[1,1,0] op_sel_hi:[0,1,1] neg_lo:[0,1,0]
	v_pk_mul_f32 v[164:165], v[122:123], v[190:191] op_sel:[0,0] op_sel_hi:[1,0]
	v_pk_fma_f32 v[122:123], v[122:123], v[186:187], v[164:165] op_sel:[1,0,0] op_sel_hi:[0,0,1] neg_lo:[0,1,0]
	v_pk_mul_f32 v[180:181], v[124:125], v[190:191] op_sel:[0,1] op_sel_hi:[1,1]
	v_pk_fma_f32 v[124:125], v[124:125], v[186:187], v[180:181] op_sel:[1,1,0] op_sel_hi:[0,1,1] neg_lo:[0,1,0]
	v_cvt_pk_bf16_f32 v172, v126, v127
	v_cvt_pk_bf16_f32 v173, v128, v129
	v_cvt_pk_bf16_f32 v174, v122, v123
	v_cvt_pk_bf16_f32 v175, v124, v125
	v_mov_b32_e32 v126, 0
	v_mov_b32_e32 v127, 0
	v_mov_b32_e32 v128, 0
	v_mov_b32_e32 v129, 0
	v_mov_b32_e32 v122, 0
	v_mov_b32_e32 v123, 0
	v_mov_b32_e32 v124, 0
	v_mov_b32_e32 v125, 0
	global_store_dwordx4 v[182:183], v[172:175], off sc1 nt
	v_pk_mul_f32 v[160:161], v[118:119], v[188:189] op_sel:[0,0] op_sel_hi:[1,0]
	v_pk_fma_f32 v[118:119], v[118:119], v[184:185], v[160:161] op_sel:[1,0,0] op_sel_hi:[0,0,1] neg_lo:[0,1,0]
	v_pk_mul_f32 v[162:163], v[120:121], v[188:189] op_sel:[0,1] op_sel_hi:[1,1]
	v_pk_fma_f32 v[120:121], v[120:121], v[184:185], v[162:163] op_sel:[1,1,0] op_sel_hi:[0,1,1] neg_lo:[0,1,0]
	v_pk_mul_f32 v[164:165], v[114:115], v[190:191] op_sel:[0,0] op_sel_hi:[1,0]
	v_pk_fma_f32 v[114:115], v[114:115], v[186:187], v[164:165] op_sel:[1,0,0] op_sel_hi:[0,0,1] neg_lo:[0,1,0]
	v_pk_mul_f32 v[180:181], v[116:117], v[190:191] op_sel:[0,1] op_sel_hi:[1,1]
	v_pk_fma_f32 v[116:117], v[116:117], v[186:187], v[180:181] op_sel:[1,1,0] op_sel_hi:[0,1,1] neg_lo:[0,1,0]
	v_cvt_pk_bf16_f32 v176, v118, v119
	v_cvt_pk_bf16_f32 v177, v120, v121
	v_cvt_pk_bf16_f32 v178, v114, v115
	v_cvt_pk_bf16_f32 v179, v116, v117
	v_mov_b32_e32 v118, 0
	v_mov_b32_e32 v119, 0
	v_mov_b32_e32 v120, 0
	v_mov_b32_e32 v121, 0
	v_mov_b32_e32 v114, 0
	v_mov_b32_e32 v115, 0
	v_mov_b32_e32 v116, 0
	v_mov_b32_e32 v117, 0
	global_store_dwordx4 v[182:183], v[176:179], off offset:256 sc1 nt
	s_waitcnt vmcnt(10)
	v_mov_b64_e32 v[182:183], s[12:13]
	v_add_u32_e32 v181, 16, v170
	v_mad_i64_i32 v[182:183], s[0:1], v181, s43, v[182:183]
	v_lshl_add_u64 v[182:183], v[158:159], 1, v[182:183]
	v_pk_mul_f32 v[160:161], v[110:111], v[196:197] op_sel:[0,0] op_sel_hi:[1,0]
	v_pk_fma_f32 v[110:111], v[110:111], v[192:193], v[160:161] op_sel:[1,0,0] op_sel_hi:[0,0,1] neg_lo:[0,1,0]
	v_pk_mul_f32 v[162:163], v[112:113], v[196:197] op_sel:[0,1] op_sel_hi:[1,1]
	v_pk_fma_f32 v[112:113], v[112:113], v[192:193], v[162:163] op_sel:[1,1,0] op_sel_hi:[0,1,1] neg_lo:[0,1,0]
	v_pk_mul_f32 v[164:165], v[106:107], v[198:199] op_sel:[0,0] op_sel_hi:[1,0]
	v_pk_fma_f32 v[106:107], v[106:107], v[194:195], v[164:165] op_sel:[1,0,0] op_sel_hi:[0,0,1] neg_lo:[0,1,0]
	v_pk_mul_f32 v[180:181], v[108:109], v[198:199] op_sel:[0,1] op_sel_hi:[1,1]
	v_pk_fma_f32 v[108:109], v[108:109], v[194:195], v[180:181] op_sel:[1,1,0] op_sel_hi:[0,1,1] neg_lo:[0,1,0]
	v_cvt_pk_bf16_f32 v172, v110, v111
	v_cvt_pk_bf16_f32 v173, v112, v113
	v_cvt_pk_bf16_f32 v174, v106, v107
	v_cvt_pk_bf16_f32 v175, v108, v109
	v_mov_b32_e32 v110, 0
	v_mov_b32_e32 v111, 0
	v_mov_b32_e32 v112, 0
	v_mov_b32_e32 v113, 0
	v_mov_b32_e32 v106, 0
	v_mov_b32_e32 v107, 0
	v_mov_b32_e32 v108, 0
	v_mov_b32_e32 v109, 0
	global_store_dwordx4 v[182:183], v[172:175], off sc1 nt
	v_pk_mul_f32 v[160:161], v[102:103], v[196:197] op_sel:[0,0] op_sel_hi:[1,0]
	v_pk_fma_f32 v[102:103], v[102:103], v[192:193], v[160:161] op_sel:[1,0,0] op_sel_hi:[0,0,1] neg_lo:[0,1,0]
	v_pk_mul_f32 v[162:163], v[104:105], v[196:197] op_sel:[0,1] op_sel_hi:[1,1]
	v_pk_fma_f32 v[104:105], v[104:105], v[192:193], v[162:163] op_sel:[1,1,0] op_sel_hi:[0,1,1] neg_lo:[0,1,0]
	v_pk_mul_f32 v[164:165], v[98:99], v[198:199] op_sel:[0,0] op_sel_hi:[1,0]
	v_pk_fma_f32 v[98:99], v[98:99], v[194:195], v[164:165] op_sel:[1,0,0] op_sel_hi:[0,0,1] neg_lo:[0,1,0]
	v_pk_mul_f32 v[180:181], v[100:101], v[198:199] op_sel:[0,1] op_sel_hi:[1,1]
	v_pk_fma_f32 v[100:101], v[100:101], v[194:195], v[180:181] op_sel:[1,1,0] op_sel_hi:[0,1,1] neg_lo:[0,1,0]
	v_cvt_pk_bf16_f32 v176, v102, v103
	v_cvt_pk_bf16_f32 v177, v104, v105
	v_cvt_pk_bf16_f32 v178, v98, v99
	v_cvt_pk_bf16_f32 v179, v100, v101
	v_mov_b32_e32 v102, 0
	v_mov_b32_e32 v103, 0
	v_mov_b32_e32 v104, 0
	v_mov_b32_e32 v105, 0
	v_mov_b32_e32 v98, 0
	v_mov_b32_e32 v99, 0
	v_mov_b32_e32 v100, 0
	v_mov_b32_e32 v101, 0
	global_store_dwordx4 v[182:183], v[176:179], off offset:256 sc1 nt
	v_add_u32_e32 v244, 0xa0, v170
	v_lshlrev_b32_e32 v244, 8, v244
	v_and_b32_e32 v244, 0x7ff00, v244
	v_lshl_add_u64 v[246:247], v[142:143], 0, v[244:245]
	global_load_dwordx4 v[184:187], v[246:247], off
	v_lshl_add_u64 v[246:247], v[144:145], 0, v[244:245]
	global_load_dwordx4 v[188:191], v[246:247], off
	v_add_u32_e32 v244, 0xb0, v170
	v_lshlrev_b32_e32 v244, 8, v244
	v_and_b32_e32 v244, 0x7ff00, v244
	v_lshl_add_u64 v[246:247], v[142:143], 0, v[244:245]
	global_load_dwordx4 v[192:195], v[246:247], off
	v_lshl_add_u64 v[246:247], v[144:145], 0, v[244:245]
	global_load_dwordx4 v[196:199], v[246:247], off
	s_waitcnt vmcnt(14)
	v_mov_b64_e32 v[182:183], s[12:13]
	v_add_u32_e32 v181, 32, v170
	v_mad_i64_i32 v[182:183], s[0:1], v181, s43, v[182:183]
	v_lshl_add_u64 v[182:183], v[158:159], 1, v[182:183]
	v_pk_mul_f32 v[160:161], v[94:95], v[216:217] op_sel:[0,0] op_sel_hi:[1,0]
	v_pk_fma_f32 v[94:95], v[94:95], v[200:201], v[160:161] op_sel:[1,0,0] op_sel_hi:[0,0,1] neg_lo:[0,1,0]
	v_pk_mul_f32 v[162:163], v[96:97], v[216:217] op_sel:[0,1] op_sel_hi:[1,1]
	v_pk_fma_f32 v[96:97], v[96:97], v[200:201], v[162:163] op_sel:[1,1,0] op_sel_hi:[0,1,1] neg_lo:[0,1,0]
	v_pk_mul_f32 v[164:165], v[90:91], v[218:219] op_sel:[0,0] op_sel_hi:[1,0]
	v_pk_fma_f32 v[90:91], v[90:91], v[202:203], v[164:165] op_sel:[1,0,0] op_sel_hi:[0,0,1] neg_lo:[0,1,0]
	v_pk_mul_f32 v[180:181], v[92:93], v[218:219] op_sel:[0,1] op_sel_hi:[1,1]
	v_pk_fma_f32 v[92:93], v[92:93], v[202:203], v[180:181] op_sel:[1,1,0] op_sel_hi:[0,1,1] neg_lo:[0,1,0]
	v_cvt_pk_bf16_f32 v172, v94, v95
	v_cvt_pk_bf16_f32 v173, v96, v97
	v_cvt_pk_bf16_f32 v174, v90, v91
	v_cvt_pk_bf16_f32 v175, v92, v93
	v_mov_b32_e32 v94, 0
	v_mov_b32_e32 v95, 0
	v_mov_b32_e32 v96, 0
	v_mov_b32_e32 v97, 0
	v_mov_b32_e32 v90, 0
	v_mov_b32_e32 v91, 0
	v_mov_b32_e32 v92, 0
	v_mov_b32_e32 v93, 0
	global_store_dwordx4 v[182:183], v[172:175], off sc1 nt
	v_pk_mul_f32 v[160:161], v[86:87], v[216:217] op_sel:[0,0] op_sel_hi:[1,0]
	v_pk_fma_f32 v[86:87], v[86:87], v[200:201], v[160:161] op_sel:[1,0,0] op_sel_hi:[0,0,1] neg_lo:[0,1,0]
	v_pk_mul_f32 v[162:163], v[88:89], v[216:217] op_sel:[0,1] op_sel_hi:[1,1]
	v_pk_fma_f32 v[88:89], v[88:89], v[200:201], v[162:163] op_sel:[1,1,0] op_sel_hi:[0,1,1] neg_lo:[0,1,0]
	v_pk_mul_f32 v[164:165], v[82:83], v[218:219] op_sel:[0,0] op_sel_hi:[1,0]
	v_pk_fma_f32 v[82:83], v[82:83], v[202:203], v[164:165] op_sel:[1,0,0] op_sel_hi:[0,0,1] neg_lo:[0,1,0]
	v_pk_mul_f32 v[180:181], v[84:85], v[218:219] op_sel:[0,1] op_sel_hi:[1,1]
	v_pk_fma_f32 v[84:85], v[84:85], v[202:203], v[180:181] op_sel:[1,1,0] op_sel_hi:[0,1,1] neg_lo:[0,1,0]
	v_cvt_pk_bf16_f32 v176, v86, v87
	v_cvt_pk_bf16_f32 v177, v88, v89
	v_cvt_pk_bf16_f32 v178, v82, v83
	v_cvt_pk_bf16_f32 v179, v84, v85
	v_mov_b32_e32 v86, 0
	v_mov_b32_e32 v87, 0
	v_mov_b32_e32 v88, 0
	v_mov_b32_e32 v89, 0
	v_mov_b32_e32 v82, 0
	v_mov_b32_e32 v83, 0
	v_mov_b32_e32 v84, 0
	v_mov_b32_e32 v85, 0
	global_store_dwordx4 v[182:183], v[176:179], off offset:256 sc1 nt
	s_waitcnt vmcnt(14)
	v_mov_b64_e32 v[182:183], s[12:13]
	v_add_u32_e32 v181, 48, v170
	v_mad_i64_i32 v[182:183], s[0:1], v181, s43, v[182:183]
	v_lshl_add_u64 v[182:183], v[158:159], 1, v[182:183]
	v_pk_mul_f32 v[160:161], v[78:79], v[224:225] op_sel:[0,0] op_sel_hi:[1,0]
	v_pk_fma_f32 v[78:79], v[78:79], v[220:221], v[160:161] op_sel:[1,0,0] op_sel_hi:[0,0,1] neg_lo:[0,1,0]
	v_pk_mul_f32 v[162:163], v[80:81], v[224:225] op_sel:[0,1] op_sel_hi:[1,1]
	v_pk_fma_f32 v[80:81], v[80:81], v[220:221], v[162:163] op_sel:[1,1,0] op_sel_hi:[0,1,1] neg_lo:[0,1,0]
	v_pk_mul_f32 v[164:165], v[74:75], v[226:227] op_sel:[0,0] op_sel_hi:[1,0]
	v_pk_fma_f32 v[74:75], v[74:75], v[222:223], v[164:165] op_sel:[1,0,0] op_sel_hi:[0,0,1] neg_lo:[0,1,0]
	v_pk_mul_f32 v[180:181], v[76:77], v[226:227] op_sel:[0,1] op_sel_hi:[1,1]
	v_pk_fma_f32 v[76:77], v[76:77], v[222:223], v[180:181] op_sel:[1,1,0] op_sel_hi:[0,1,1] neg_lo:[0,1,0]
	v_cvt_pk_bf16_f32 v172, v78, v79
	v_cvt_pk_bf16_f32 v173, v80, v81
	v_cvt_pk_bf16_f32 v174, v74, v75
	v_cvt_pk_bf16_f32 v175, v76, v77
	v_mov_b32_e32 v78, 0
	v_mov_b32_e32 v79, 0
	v_mov_b32_e32 v80, 0
	v_mov_b32_e32 v81, 0
	v_mov_b32_e32 v74, 0
	v_mov_b32_e32 v75, 0
	v_mov_b32_e32 v76, 0
	v_mov_b32_e32 v77, 0
	global_store_dwordx4 v[182:183], v[172:175], off sc1 nt
	v_pk_mul_f32 v[160:161], v[70:71], v[224:225] op_sel:[0,0] op_sel_hi:[1,0]
	v_pk_fma_f32 v[70:71], v[70:71], v[220:221], v[160:161] op_sel:[1,0,0] op_sel_hi:[0,0,1] neg_lo:[0,1,0]
	v_pk_mul_f32 v[162:163], v[72:73], v[224:225] op_sel:[0,1] op_sel_hi:[1,1]
	v_pk_fma_f32 v[72:73], v[72:73], v[220:221], v[162:163] op_sel:[1,1,0] op_sel_hi:[0,1,1] neg_lo:[0,1,0]
	v_pk_mul_f32 v[164:165], v[66:67], v[226:227] op_sel:[0,0] op_sel_hi:[1,0]
	v_pk_fma_f32 v[66:67], v[66:67], v[222:223], v[164:165] op_sel:[1,0,0] op_sel_hi:[0,0,1] neg_lo:[0,1,0]
	v_pk_mul_f32 v[180:181], v[68:69], v[226:227] op_sel:[0,1] op_sel_hi:[1,1]
	v_pk_fma_f32 v[68:69], v[68:69], v[222:223], v[180:181] op_sel:[1,1,0] op_sel_hi:[0,1,1] neg_lo:[0,1,0]
	v_cvt_pk_bf16_f32 v176, v70, v71
	v_cvt_pk_bf16_f32 v177, v72, v73
	v_cvt_pk_bf16_f32 v178, v66, v67
	v_cvt_pk_bf16_f32 v179, v68, v69
	v_mov_b32_e32 v70, 0
	v_mov_b32_e32 v71, 0
	v_mov_b32_e32 v72, 0
	v_mov_b32_e32 v73, 0
	v_mov_b32_e32 v66, 0
	v_mov_b32_e32 v67, 0
	v_mov_b32_e32 v68, 0
	v_mov_b32_e32 v69, 0
	global_store_dwordx4 v[182:183], v[176:179], off offset:256 sc1 nt
	s_waitcnt vmcnt(14)
	v_mov_b64_e32 v[182:183], s[12:13]
	v_add_u32_e32 v181, 0x80, v170
	v_mad_i64_i32 v[182:183], s[0:1], v181, s43, v[182:183]
	v_lshl_add_u64 v[182:183], v[158:159], 1, v[182:183]
	v_pk_mul_f32 v[160:161], v[62:63], v[232:233] op_sel:[0,0] op_sel_hi:[1,0]
	v_pk_fma_f32 v[62:63], v[62:63], v[228:229], v[160:161] op_sel:[1,0,0] op_sel_hi:[0,0,1] neg_lo:[0,1,0]
	v_pk_mul_f32 v[162:163], v[64:65], v[232:233] op_sel:[0,1] op_sel_hi:[1,1]
	v_pk_fma_f32 v[64:65], v[64:65], v[228:229], v[162:163] op_sel:[1,1,0] op_sel_hi:[0,1,1] neg_lo:[0,1,0]
	v_pk_mul_f32 v[164:165], v[58:59], v[234:235] op_sel:[0,0] op_sel_hi:[1,0]
	v_pk_fma_f32 v[58:59], v[58:59], v[230:231], v[164:165] op_sel:[1,0,0] op_sel_hi:[0,0,1] neg_lo:[0,1,0]
	v_pk_mul_f32 v[180:181], v[60:61], v[234:235] op_sel:[0,1] op_sel_hi:[1,1]
	v_pk_fma_f32 v[60:61], v[60:61], v[230:231], v[180:181] op_sel:[1,1,0] op_sel_hi:[0,1,1] neg_lo:[0,1,0]
	v_cvt_pk_bf16_f32 v172, v62, v63
	v_cvt_pk_bf16_f32 v173, v64, v65
	v_cvt_pk_bf16_f32 v174, v58, v59
	v_cvt_pk_bf16_f32 v175, v60, v61
	v_mov_b32_e32 v62, 0
	v_mov_b32_e32 v63, 0
	v_mov_b32_e32 v64, 0
	v_mov_b32_e32 v65, 0
	v_mov_b32_e32 v58, 0
	v_mov_b32_e32 v59, 0
	v_mov_b32_e32 v60, 0
	v_mov_b32_e32 v61, 0
	global_store_dwordx4 v[182:183], v[172:175], off sc1 nt
	v_pk_mul_f32 v[160:161], v[54:55], v[232:233] op_sel:[0,0] op_sel_hi:[1,0]
	v_pk_fma_f32 v[54:55], v[54:55], v[228:229], v[160:161] op_sel:[1,0,0] op_sel_hi:[0,0,1] neg_lo:[0,1,0]
	v_pk_mul_f32 v[162:163], v[56:57], v[232:233] op_sel:[0,1] op_sel_hi:[1,1]
	v_pk_fma_f32 v[56:57], v[56:57], v[228:229], v[162:163] op_sel:[1,1,0] op_sel_hi:[0,1,1] neg_lo:[0,1,0]
	v_pk_mul_f32 v[164:165], v[50:51], v[234:235] op_sel:[0,0] op_sel_hi:[1,0]
	v_pk_fma_f32 v[50:51], v[50:51], v[230:231], v[164:165] op_sel:[1,0,0] op_sel_hi:[0,0,1] neg_lo:[0,1,0]
	v_pk_mul_f32 v[180:181], v[52:53], v[234:235] op_sel:[0,1] op_sel_hi:[1,1]
	v_pk_fma_f32 v[52:53], v[52:53], v[230:231], v[180:181] op_sel:[1,1,0] op_sel_hi:[0,1,1] neg_lo:[0,1,0]
	v_cvt_pk_bf16_f32 v176, v54, v55
	v_cvt_pk_bf16_f32 v177, v56, v57
	v_cvt_pk_bf16_f32 v178, v50, v51
	v_cvt_pk_bf16_f32 v179, v52, v53
	v_mov_b32_e32 v54, 0
	v_mov_b32_e32 v55, 0
	v_mov_b32_e32 v56, 0
	v_mov_b32_e32 v57, 0
	v_mov_b32_e32 v50, 0
	v_mov_b32_e32 v51, 0
	v_mov_b32_e32 v52, 0
	v_mov_b32_e32 v53, 0
	global_store_dwordx4 v[182:183], v[176:179], off offset:256 sc1 nt
	s_waitcnt vmcnt(14)
	v_mov_b64_e32 v[182:183], s[12:13]
	v_add_u32_e32 v181, 0x90, v170
	v_mad_i64_i32 v[182:183], s[0:1], v181, s43, v[182:183]
	v_lshl_add_u64 v[182:183], v[158:159], 1, v[182:183]
	v_pk_mul_f32 v[160:161], v[46:47], v[240:241] op_sel:[0,0] op_sel_hi:[1,0]
	v_pk_fma_f32 v[46:47], v[46:47], v[236:237], v[160:161] op_sel:[1,0,0] op_sel_hi:[0,0,1] neg_lo:[0,1,0]
	v_pk_mul_f32 v[162:163], v[48:49], v[240:241] op_sel:[0,1] op_sel_hi:[1,1]
	v_pk_fma_f32 v[48:49], v[48:49], v[236:237], v[162:163] op_sel:[1,1,0] op_sel_hi:[0,1,1] neg_lo:[0,1,0]
	v_pk_mul_f32 v[164:165], v[42:43], v[242:243] op_sel:[0,0] op_sel_hi:[1,0]
	v_pk_fma_f32 v[42:43], v[42:43], v[238:239], v[164:165] op_sel:[1,0,0] op_sel_hi:[0,0,1] neg_lo:[0,1,0]
	v_pk_mul_f32 v[180:181], v[44:45], v[242:243] op_sel:[0,1] op_sel_hi:[1,1]
	v_pk_fma_f32 v[44:45], v[44:45], v[238:239], v[180:181] op_sel:[1,1,0] op_sel_hi:[0,1,1] neg_lo:[0,1,0]
	v_cvt_pk_bf16_f32 v172, v46, v47
	v_cvt_pk_bf16_f32 v173, v48, v49
	v_cvt_pk_bf16_f32 v174, v42, v43
	v_cvt_pk_bf16_f32 v175, v44, v45
	v_mov_b32_e32 v46, 0
	v_mov_b32_e32 v47, 0
	v_mov_b32_e32 v48, 0
	v_mov_b32_e32 v49, 0
	v_mov_b32_e32 v42, 0
	v_mov_b32_e32 v43, 0
	v_mov_b32_e32 v44, 0
	v_mov_b32_e32 v45, 0
	global_store_dwordx4 v[182:183], v[172:175], off sc1 nt
	v_pk_mul_f32 v[160:161], v[38:39], v[240:241] op_sel:[0,0] op_sel_hi:[1,0]
	v_pk_fma_f32 v[38:39], v[38:39], v[236:237], v[160:161] op_sel:[1,0,0] op_sel_hi:[0,0,1] neg_lo:[0,1,0]
	v_pk_mul_f32 v[162:163], v[40:41], v[240:241] op_sel:[0,1] op_sel_hi:[1,1]
	v_pk_fma_f32 v[40:41], v[40:41], v[236:237], v[162:163] op_sel:[1,1,0] op_sel_hi:[0,1,1] neg_lo:[0,1,0]
	v_pk_mul_f32 v[164:165], v[34:35], v[242:243] op_sel:[0,0] op_sel_hi:[1,0]
	v_pk_fma_f32 v[34:35], v[34:35], v[238:239], v[164:165] op_sel:[1,0,0] op_sel_hi:[0,0,1] neg_lo:[0,1,0]
	v_pk_mul_f32 v[180:181], v[36:37], v[242:243] op_sel:[0,1] op_sel_hi:[1,1]
	v_pk_fma_f32 v[36:37], v[36:37], v[238:239], v[180:181] op_sel:[1,1,0] op_sel_hi:[0,1,1] neg_lo:[0,1,0]
	v_cvt_pk_bf16_f32 v176, v38, v39
	v_cvt_pk_bf16_f32 v177, v40, v41
	v_cvt_pk_bf16_f32 v178, v34, v35
	v_cvt_pk_bf16_f32 v179, v36, v37
	v_mov_b32_e32 v38, 0
	v_mov_b32_e32 v39, 0
	v_mov_b32_e32 v40, 0
	v_mov_b32_e32 v41, 0
	v_mov_b32_e32 v34, 0
	v_mov_b32_e32 v35, 0
	v_mov_b32_e32 v36, 0
	v_mov_b32_e32 v37, 0
	global_store_dwordx4 v[182:183], v[176:179], off offset:256 sc1 nt
	s_waitcnt vmcnt(10)
	v_mov_b64_e32 v[182:183], s[12:13]
	v_add_u32_e32 v181, 0xa0, v170
	v_mad_i64_i32 v[182:183], s[0:1], v181, s43, v[182:183]
	v_lshl_add_u64 v[182:183], v[158:159], 1, v[182:183]
	v_pk_mul_f32 v[160:161], v[30:31], v[188:189] op_sel:[0,0] op_sel_hi:[1,0]
	v_pk_fma_f32 v[30:31], v[30:31], v[184:185], v[160:161] op_sel:[1,0,0] op_sel_hi:[0,0,1] neg_lo:[0,1,0]
	v_pk_mul_f32 v[162:163], v[32:33], v[188:189] op_sel:[0,1] op_sel_hi:[1,1]
	v_pk_fma_f32 v[32:33], v[32:33], v[184:185], v[162:163] op_sel:[1,1,0] op_sel_hi:[0,1,1] neg_lo:[0,1,0]
	v_pk_mul_f32 v[164:165], v[26:27], v[190:191] op_sel:[0,0] op_sel_hi:[1,0]
	v_pk_fma_f32 v[26:27], v[26:27], v[186:187], v[164:165] op_sel:[1,0,0] op_sel_hi:[0,0,1] neg_lo:[0,1,0]
	v_pk_mul_f32 v[180:181], v[28:29], v[190:191] op_sel:[0,1] op_sel_hi:[1,1]
	v_pk_fma_f32 v[28:29], v[28:29], v[186:187], v[180:181] op_sel:[1,1,0] op_sel_hi:[0,1,1] neg_lo:[0,1,0]
	v_cvt_pk_bf16_f32 v172, v30, v31
	v_cvt_pk_bf16_f32 v173, v32, v33
	v_cvt_pk_bf16_f32 v174, v26, v27
	v_cvt_pk_bf16_f32 v175, v28, v29
	v_mov_b32_e32 v30, 0
	v_mov_b32_e32 v31, 0
	v_mov_b32_e32 v32, 0
	v_mov_b32_e32 v33, 0
	v_mov_b32_e32 v26, 0
	v_mov_b32_e32 v27, 0
	v_mov_b32_e32 v28, 0
	v_mov_b32_e32 v29, 0
	global_store_dwordx4 v[182:183], v[172:175], off sc1 nt
	v_pk_mul_f32 v[160:161], v[22:23], v[188:189] op_sel:[0,0] op_sel_hi:[1,0]
	v_pk_fma_f32 v[22:23], v[22:23], v[184:185], v[160:161] op_sel:[1,0,0] op_sel_hi:[0,0,1] neg_lo:[0,1,0]
	v_pk_mul_f32 v[162:163], v[24:25], v[188:189] op_sel:[0,1] op_sel_hi:[1,1]
	v_pk_fma_f32 v[24:25], v[24:25], v[184:185], v[162:163] op_sel:[1,1,0] op_sel_hi:[0,1,1] neg_lo:[0,1,0]
	v_pk_mul_f32 v[164:165], v[18:19], v[190:191] op_sel:[0,0] op_sel_hi:[1,0]
	v_pk_fma_f32 v[18:19], v[18:19], v[186:187], v[164:165] op_sel:[1,0,0] op_sel_hi:[0,0,1] neg_lo:[0,1,0]
	v_pk_mul_f32 v[180:181], v[20:21], v[190:191] op_sel:[0,1] op_sel_hi:[1,1]
	v_pk_fma_f32 v[20:21], v[20:21], v[186:187], v[180:181] op_sel:[1,1,0] op_sel_hi:[0,1,1] neg_lo:[0,1,0]
	v_cvt_pk_bf16_f32 v176, v22, v23
	v_cvt_pk_bf16_f32 v177, v24, v25
	v_cvt_pk_bf16_f32 v178, v18, v19
	v_cvt_pk_bf16_f32 v179, v20, v21
	v_mov_b32_e32 v22, 0
	v_mov_b32_e32 v23, 0
	v_mov_b32_e32 v24, 0
	v_mov_b32_e32 v25, 0
	v_mov_b32_e32 v18, 0
	v_mov_b32_e32 v19, 0
	v_mov_b32_e32 v20, 0
	v_mov_b32_e32 v21, 0
	global_store_dwordx4 v[182:183], v[176:179], off offset:256 sc1 nt
	s_waitcnt vmcnt(10)
	v_mov_b64_e32 v[182:183], s[12:13]
	v_add_u32_e32 v181, 0xb0, v170
	v_mad_i64_i32 v[182:183], s[0:1], v181, s43, v[182:183]
	v_lshl_add_u64 v[182:183], v[158:159], 1, v[182:183]
	v_pk_mul_f32 v[160:161], v[14:15], v[196:197] op_sel:[0,0] op_sel_hi:[1,0]
	v_pk_fma_f32 v[14:15], v[14:15], v[192:193], v[160:161] op_sel:[1,0,0] op_sel_hi:[0,0,1] neg_lo:[0,1,0]
	v_pk_mul_f32 v[162:163], v[16:17], v[196:197] op_sel:[0,1] op_sel_hi:[1,1]
	v_pk_fma_f32 v[16:17], v[16:17], v[192:193], v[162:163] op_sel:[1,1,0] op_sel_hi:[0,1,1] neg_lo:[0,1,0]
	v_pk_mul_f32 v[164:165], v[10:11], v[198:199] op_sel:[0,0] op_sel_hi:[1,0]
	v_pk_fma_f32 v[10:11], v[10:11], v[194:195], v[164:165] op_sel:[1,0,0] op_sel_hi:[0,0,1] neg_lo:[0,1,0]
	v_pk_mul_f32 v[180:181], v[12:13], v[198:199] op_sel:[0,1] op_sel_hi:[1,1]
	v_pk_fma_f32 v[12:13], v[12:13], v[194:195], v[180:181] op_sel:[1,1,0] op_sel_hi:[0,1,1] neg_lo:[0,1,0]
	v_cvt_pk_bf16_f32 v172, v14, v15
	v_cvt_pk_bf16_f32 v173, v16, v17
	v_cvt_pk_bf16_f32 v174, v10, v11
	v_cvt_pk_bf16_f32 v175, v12, v13
	v_mov_b32_e32 v14, 0
	v_mov_b32_e32 v15, 0
	v_mov_b32_e32 v16, 0
	v_mov_b32_e32 v17, 0
	v_mov_b32_e32 v10, 0
	v_mov_b32_e32 v11, 0
	v_mov_b32_e32 v12, 0
	v_mov_b32_e32 v13, 0
	global_store_dwordx4 v[182:183], v[172:175], off sc1 nt
	v_pk_mul_f32 v[160:161], v[6:7], v[196:197] op_sel:[0,0] op_sel_hi:[1,0]
	v_pk_fma_f32 v[6:7], v[6:7], v[192:193], v[160:161] op_sel:[1,0,0] op_sel_hi:[0,0,1] neg_lo:[0,1,0]
	v_pk_mul_f32 v[162:163], v[8:9], v[196:197] op_sel:[0,1] op_sel_hi:[1,1]
	v_pk_fma_f32 v[8:9], v[8:9], v[192:193], v[162:163] op_sel:[1,1,0] op_sel_hi:[0,1,1] neg_lo:[0,1,0]
	v_pk_mul_f32 v[164:165], v[2:3], v[198:199] op_sel:[0,0] op_sel_hi:[1,0]
	v_pk_fma_f32 v[2:3], v[2:3], v[194:195], v[164:165] op_sel:[1,0,0] op_sel_hi:[0,0,1] neg_lo:[0,1,0]
	v_pk_mul_f32 v[180:181], v[4:5], v[198:199] op_sel:[0,1] op_sel_hi:[1,1]
	v_pk_fma_f32 v[4:5], v[4:5], v[194:195], v[180:181] op_sel:[1,1,0] op_sel_hi:[0,1,1] neg_lo:[0,1,0]
	v_cvt_pk_bf16_f32 v176, v6, v7
	v_cvt_pk_bf16_f32 v177, v8, v9
	v_cvt_pk_bf16_f32 v178, v2, v3
	v_cvt_pk_bf16_f32 v179, v4, v5
	v_mov_b32_e32 v6, 0
	v_mov_b32_e32 v7, 0
	v_mov_b32_e32 v8, 0
	v_mov_b32_e32 v9, 0
	v_mov_b32_e32 v2, 0
	v_mov_b32_e32 v3, 0
	v_mov_b32_e32 v4, 0
	v_mov_b32_e32 v5, 0
	global_store_dwordx4 v[182:183], v[176:179], off offset:256 sc1 nt
.Lepi_join:
	s_andn2_b64 vcc, exec, s[4:5]
	s_cbranch_vccz .Lepi_trail_in
	s_barrier
	s_andn2_b64 vcc, exec, s[6:7]
	s_mov_b64 s[0:1], -1
	s_cbranch_vccnz .LBB0_136
	s_branch .LBB0_135
.Lepi_trail_in:
	s_andn2_b64 vcc, exec, s[6:7]
	s_mov_b64 s[0:1], -1
	s_cbranch_vccnz .LBB0_136
	s_barrier
	s_branch .LBB0_135

.LBB0_775:
	v_lshl_add_u32 v146, s56, 8, v142
	v_lshl_or_b32 v140, s55, 8, v144
	v_ashrrev_i32_e32 v147, 31, v146
	v_ashrrev_i32_e32 v141, 31, v140
	v_lshlrev_b64 v[156:157], 12, v[146:147]
	v_lshl_add_u64 v[156:157], s[8:9], 0, v[156:157]
	v_lshlrev_b64 v[158:159], 1, v[140:141]
	v_lshl_add_u64 v[140:141], v[156:157], 0, v[158:159]
	v_cvt_pk_bf16_f32 v126, v126, v127
	v_cvt_pk_bf16_f32 v127, v128, v129
	v_cvt_pk_bf16_f32 v128, v122, v123
	v_cvt_pk_bf16_f32 v129, v124, v125
	global_store_dwordx4 v[140:141], v[126:129], off
	v_cvt_pk_bf16_f32 v114, v114, v115
	v_cvt_pk_bf16_f32 v115, v116, v117
	v_cvt_pk_bf16_f32 v116, v106, v107
	v_or_b32_e32 v106, 16, v146
	v_ashrrev_i32_e32 v107, 31, v106
	v_lshlrev_b64 v[106:107], 12, v[106:107]
	v_lshl_add_u64 v[106:107], s[8:9], 0, v[106:107]
	v_cvt_pk_bf16_f32 v117, v108, v109
	global_store_dwordx4 v[140:141], v[114:117], off offset:256
	s_mov_b64 s[0:1], 0x80000
	v_readlane_b32 s60, v254, 37
	v_lshl_add_u64 v[114:115], v[106:107], 0, v[158:159]
	v_cvt_pk_bf16_f32 v106, v118, v119
	v_cvt_pk_bf16_f32 v107, v120, v121
	v_cvt_pk_bf16_f32 v108, v110, v111
	v_cvt_pk_bf16_f32 v109, v112, v113
	global_store_dwordx4 v[114:115], v[106:109], off
	v_cvt_pk_bf16_f32 v98, v98, v99
	v_cvt_pk_bf16_f32 v99, v100, v101
	v_cvt_pk_bf16_f32 v100, v90, v91
	v_or_b32_e32 v90, 32, v146
	v_ashrrev_i32_e32 v91, 31, v90
	v_lshlrev_b64 v[90:91], 12, v[90:91]
	v_lshl_add_u64 v[90:91], s[8:9], 0, v[90:91]
	v_cvt_pk_bf16_f32 v101, v92, v93
	global_store_dwordx4 v[114:115], v[98:101], off offset:256
	v_readlane_b32 s61, v254, 38
	s_nop 0
	v_lshl_add_u64 v[98:99], v[90:91], 0, v[158:159]
	v_cvt_pk_bf16_f32 v90, v102, v103
	v_cvt_pk_bf16_f32 v91, v104, v105
	v_cvt_pk_bf16_f32 v92, v94, v95
	v_cvt_pk_bf16_f32 v93, v96, v97
	global_store_dwordx4 v[98:99], v[90:93], off
	v_cvt_pk_bf16_f32 v82, v82, v83
	v_cvt_pk_bf16_f32 v83, v84, v85
	v_cvt_pk_bf16_f32 v84, v74, v75
	v_or_b32_e32 v74, 48, v146
	v_ashrrev_i32_e32 v75, 31, v74
	v_lshlrev_b64 v[74:75], 12, v[74:75]
	v_lshl_add_u64 v[74:75], s[8:9], 0, v[74:75]
	v_cvt_pk_bf16_f32 v85, v76, v77
	global_store_dwordx4 v[98:99], v[82:85], off offset:256
	s_nop 1
	v_lshl_add_u64 v[82:83], v[74:75], 0, v[158:159]
	v_cvt_pk_bf16_f32 v74, v86, v87
	v_cvt_pk_bf16_f32 v75, v88, v89
	v_cvt_pk_bf16_f32 v76, v78, v79
	v_cvt_pk_bf16_f32 v77, v80, v81
	global_store_dwordx4 v[82:83], v[74:77], off
	v_cvt_pk_bf16_f32 v70, v70, v71
	v_cvt_pk_bf16_f32 v71, v72, v73
	v_cvt_pk_bf16_f32 v72, v66, v67
	v_lshl_add_u64 v[66:67], v[140:141], 0, s[0:1]
	s_mov_b32 s0, 0x80000
	v_cvt_pk_bf16_f32 v73, v68, v69
	global_store_dwordx4 v[82:83], v[70:73], off offset:256
	v_cvt_pk_bf16_f32 v62, v62, v63
	v_cvt_pk_bf16_f32 v63, v64, v65
	v_cvt_pk_bf16_f32 v64, v58, v59
	v_add_co_u32_e32 v58, vcc, s0, v140
	v_cvt_pk_bf16_f32 v65, v60, v61
	s_mov_b64 s[0:1], 0x90000
	s_nop 0
	v_addc_co_u32_e32 v59, vcc, 0, v141, vcc
	global_store_dwordx4 v[58:59], v[62:65], off
	v_cvt_pk_bf16_f32 v50, v50, v51
	v_cvt_pk_bf16_f32 v51, v52, v53
	v_cvt_pk_bf16_f32 v52, v42, v43
	v_cvt_pk_bf16_f32 v53, v44, v45
	global_store_dwordx4 v[66:67], v[50:53], off offset:256
	v_cvt_pk_bf16_f32 v42, v54, v55
	v_cvt_pk_bf16_f32 v43, v56, v57
	v_cvt_pk_bf16_f32 v44, v46, v47
	v_cvt_pk_bf16_f32 v45, v48, v49
	s_nop 1
	v_lshl_add_u64 v[50:51], v[140:141], 0, s[0:1]
	s_mov_b32 s0, 0x90000
	v_add_co_u32_e32 v46, vcc, s0, v140
	s_mov_b64 s[0:1], 0xa0000
	s_nop 0
	v_addc_co_u32_e32 v47, vcc, 0, v141, vcc
	global_store_dwordx4 v[46:47], v[42:45], off
	v_cvt_pk_bf16_f32 v34, v34, v35
	v_cvt_pk_bf16_f32 v35, v36, v37
	v_cvt_pk_bf16_f32 v36, v26, v27
	v_cvt_pk_bf16_f32 v37, v28, v29
	global_store_dwordx4 v[50:51], v[34:37], off offset:256
	v_cvt_pk_bf16_f32 v26, v38, v39
	v_cvt_pk_bf16_f32 v27, v40, v41
	v_cvt_pk_bf16_f32 v28, v30, v31
	v_cvt_pk_bf16_f32 v29, v32, v33
	s_nop 1
	v_lshl_add_u64 v[34:35], v[140:141], 0, s[0:1]
	s_mov_b32 s0, 0xa0000
	v_add_co_u32_e32 v30, vcc, s0, v140
	s_mov_b64 s[0:1], 0xb0000
	s_nop 0
	v_addc_co_u32_e32 v31, vcc, 0, v141, vcc
	global_store_dwordx4 v[30:31], v[26:29], off
	v_cvt_pk_bf16_f32 v18, v18, v19
	v_cvt_pk_bf16_f32 v19, v20, v21
	v_cvt_pk_bf16_f32 v20, v10, v11
	v_cvt_pk_bf16_f32 v21, v12, v13
	global_store_dwordx4 v[34:35], v[18:21], off offset:256
	v_cvt_pk_bf16_f32 v10, v22, v23
	v_cvt_pk_bf16_f32 v11, v24, v25
	v_cvt_pk_bf16_f32 v12, v14, v15
	v_cvt_pk_bf16_f32 v13, v16, v17
	s_nop 1
	v_lshl_add_u64 v[18:19], v[140:141], 0, s[0:1]
	s_mov_b32 s0, 0xb0000
	v_add_co_u32_e32 v14, vcc, s0, v140
	s_mov_b64 s[0:1], -1
	s_nop 0
	v_addc_co_u32_e32 v15, vcc, 0, v141, vcc
	s_andn2_b64 vcc, exec, s[6:7]
	global_store_dwordx4 v[14:15], v[10:13], off
	v_cvt_pk_bf16_f32 v6, v6, v7
	v_cvt_pk_bf16_f32 v7, v8, v9
	v_cvt_pk_bf16_f32 v8, v2, v3
	v_cvt_pk_bf16_f32 v9, v4, v5
	global_store_dwordx4 v[18:19], v[6:9], off offset:256
	s_andn2_b64 vcc, exec, s[4:5]
	s_cbranch_vccz .Lepi_trail_out
	s_barrier
	s_andn2_b64 vcc, exec, s[6:7]
	s_cbranch_vccnz .LBB0_764
	s_branch .LBB0_763
.Lepi_trail_out:
	s_andn2_b64 vcc, exec, s[6:7]
	s_cbranch_vccnz .LBB0_764
	s_barrier
	s_branch .LBB0_763
